# PIN4: per-loop placement pin: GEMM1 K-loop/epilogue/tail code moved to the other 8-byte phase (4-byte pads before the K-loop and before the attention phase), other loops as in the final
# speedup vs baseline: 1.0071x; 1.0071x over previous
;     __device__ bool next(int i, Unit& u) const { const long L = (long)i * G + c; if (L >= hi) return false; unit_of((int)L, u); return true; }
; template <class Epi, bool SPLITA>
; __device__ __forceinline__ void gemm_phase(LAS unsigned char* lds, const Gemm g, const StaticOrder& S, const Epi& E) {
;     ...
;         const bool has_next = S.next(ui + 1, nxt);
;         const int npm = has_next ? nxt.pm : cur.pm; const char* nB = has_next ? (const char*)g.Bt + (size_t)nxt.pn * tstep : cB;
;         for (int t = 0; t < nt; t += 2) {
;             const bool last = (t == nt - 2);
;             const int pm2 = last ? npm : cur.pm, kt2 = last ? 0 : t + 2;
;             const char* b2 = last ? nB : cB + (size_t)(t + 2) * kstep; const char* b3 = b2 + kstep;
.LBB0_208:
	s_add_u32 s52, s0, 0x100
	s_addc_u32 s53, s1, 0
	s_ashr_i32 s67, s66, 31
	s_lshl_b64 s[10:11], s[66:67], 19
	s_add_u32 s68, s96, s10
	s_addc_u32 s69, s97, s11
	s_and_b64 s[10:11], s[6:7], exec
	s_cselect_b32 s67, s69, s1
	s_cselect_b32 s79, s68, s0
	s_ashr_i32 s71, s70, 31
	s_lshl_b64 s[0:1], s[70:71], 19
	v_lshl_add_u64 v[130:131], v[158:159], 0, s[0:1]
	v_lshl_add_u64 v[132:133], v[160:161], 0, s[0:1]
	s_mov_b32 s71, -2
	s_mov_b64 s[0:1], 0
	s_nop 0

; __device__ __forceinline__ void xcd_barrier(const XcdBarrier& b) {
;     ...
;     }
;     __syncthreads();
.LBB0_383:
	s_or_b64 exec, exec, s[0:1]
	s_waitcnt lgkmcnt(0)
	s_barrier
	s_nop 0
